# speedup vs baseline: 1.0157x; 1.0010x over previous
.LBB0_421:
	v_cndmask_b32_e64 v204, v162, v204, s[8:9]
	v_mul_f32_e32 v160, 0xbe0293ee, v204
	v_mov_b32_e32 v156, v160
	v_fmamk_f32 v80, v80, 0x3e0293ee, v160
	v_fmamk_f32 v81, v81, 0x3e0293ee, v160
	v_fmamk_f32 v82, v82, 0x3e0293ee, v160
	v_fmamk_f32 v83, v83, 0x3e0293ee, v160
	v_fmamk_f32 v84, v84, 0x3e0293ee, v160
	v_fmamk_f32 v85, v85, 0x3e0293ee, v160
	v_fmamk_f32 v86, v86, 0x3e0293ee, v160
	v_fmamk_f32 v87, v87, 0x3e0293ee, v160
	v_fmamk_f32 v88, v88, 0x3e0293ee, v160
	v_fmamk_f32 v89, v89, 0x3e0293ee, v160
	v_fmamk_f32 v90, v90, 0x3e0293ee, v160
	v_fmamk_f32 v91, v91, 0x3e0293ee, v160
	v_fmamk_f32 v92, v92, 0x3e0293ee, v160
	v_fmamk_f32 v93, v93, 0x3e0293ee, v160
	v_fmamk_f32 v94, v94, 0x3e0293ee, v160
	v_fmac_f32_e32 v156, 0x3e0293ee, v95
	v_exp_f32_e32 v162, v80
	v_exp_f32_e32 v224, v81
	v_exp_f32_e32 v163, v82
	v_exp_f32_e32 v223, v83
	v_exp_f32_e32 v164, v84
	v_exp_f32_e32 v222, v85
	v_exp_f32_e32 v165, v86
	v_exp_f32_e32 v207, v87
	v_exp_f32_e32 v166, v88
	v_exp_f32_e32 v173, v89
	v_exp_f32_e32 v167, v90
	v_exp_f32_e32 v172, v91
	v_exp_f32_e32 v168, v92
	v_exp_f32_e32 v171, v93
	v_exp_f32_e32 v169, v94
	v_exp_f32_e32 v170, v156
	v_pk_fma_f32 v[146:147], v[78:79], s[74:75], v[160:161] op_sel_hi:[1,0,0]
	v_pk_fma_f32 v[148:149], v[76:77], s[74:75], v[160:161] op_sel_hi:[1,0,0]
	v_pk_fma_f32 v[150:151], v[74:75], s[74:75], v[160:161] op_sel_hi:[1,0,0]
	v_pk_fma_f32 v[152:153], v[72:73], s[74:75], v[160:161] op_sel_hi:[1,0,0]
	v_pk_fma_f32 v[154:155], v[70:71], s[74:75], v[160:161] op_sel_hi:[1,0,0]
	v_pk_fma_f32 v[156:157], v[68:69], s[74:75], v[160:161] op_sel_hi:[1,0,0]
	v_pk_fma_f32 v[158:159], v[66:67], s[74:75], v[160:161] op_sel_hi:[1,0,0]
	v_pk_fma_f32 v[160:161], v[64:65], s[74:75], v[160:161] op_sel_hi:[1,0,0]
	v_add_f32_e32 v64, v225, v226
	v_fmac_f32_e32 v64, v203, v188
	v_add_f32_e32 v188, v228, v229
	s_add_i32 s0, s98, 2
	s_addk_i32 s4, 0x80
	v_fmac_f32_e32 v188, v64, v227
	s_cmp_ge_i32 s0, s82
	v_lshl_add_u64 v[180:181], v[180:181], 0, s[78:79]
	s_waitcnt lgkmcnt(0)
	s_cbranch_scc1 .Lrot_exit_405
	s_mov_b64 s[18:19], s[98:99]
	v_mov_b32_e32 v203, v174
	s_barrier
	s_branch .LBB0_405
.Lrot_exit_405:
	s_barrier
	s_branch .LBB0_424

.LBB0_446:
	v_cndmask_b32_e64 v170, v163, v203, s[8:9]
	v_mul_f32_e32 v160, 0xbe0293ee, v170
	v_mov_b32_e32 v156, v160
	v_fmamk_f32 v80, v80, 0x3e0293ee, v160
	v_fmamk_f32 v81, v81, 0x3e0293ee, v160
	v_fmamk_f32 v82, v82, 0x3e0293ee, v160
	v_fmamk_f32 v83, v83, 0x3e0293ee, v160
	v_fmamk_f32 v84, v84, 0x3e0293ee, v160
	v_fmamk_f32 v85, v85, 0x3e0293ee, v160
	v_fmamk_f32 v86, v86, 0x3e0293ee, v160
	v_fmamk_f32 v87, v87, 0x3e0293ee, v160
	v_fmamk_f32 v88, v88, 0x3e0293ee, v160
	v_fmamk_f32 v89, v89, 0x3e0293ee, v160
	v_fmamk_f32 v90, v90, 0x3e0293ee, v160
	v_fmamk_f32 v91, v91, 0x3e0293ee, v160
	v_fmamk_f32 v92, v92, 0x3e0293ee, v160
	v_fmamk_f32 v93, v93, 0x3e0293ee, v160
	v_fmamk_f32 v94, v94, 0x3e0293ee, v160
	v_fmac_f32_e32 v156, 0x3e0293ee, v95
	v_exp_f32_e32 v206, v80
	v_exp_f32_e32 v222, v81
	v_exp_f32_e32 v163, v82
	v_exp_f32_e32 v207, v83
	v_exp_f32_e32 v164, v84
	v_exp_f32_e32 v205, v85
	v_exp_f32_e32 v165, v86
	v_exp_f32_e32 v204, v87
	v_exp_f32_e32 v166, v88
	v_exp_f32_e32 v203, v89
	v_exp_f32_e32 v167, v90
	v_exp_f32_e32 v173, v91
	v_exp_f32_e32 v168, v92
	v_exp_f32_e32 v172, v93
	v_exp_f32_e32 v169, v94
	v_exp_f32_e32 v171, v156
	v_pk_fma_f32 v[146:147], v[78:79], s[74:75], v[160:161] op_sel_hi:[1,0,0]
	v_pk_fma_f32 v[148:149], v[76:77], s[74:75], v[160:161] op_sel_hi:[1,0,0]
	v_pk_fma_f32 v[150:151], v[74:75], s[74:75], v[160:161] op_sel_hi:[1,0,0]
	v_pk_fma_f32 v[152:153], v[72:73], s[74:75], v[160:161] op_sel_hi:[1,0,0]
	v_pk_fma_f32 v[154:155], v[70:71], s[74:75], v[160:161] op_sel_hi:[1,0,0]
	v_pk_fma_f32 v[156:157], v[68:69], s[74:75], v[160:161] op_sel_hi:[1,0,0]
	v_pk_fma_f32 v[158:159], v[66:67], s[74:75], v[160:161] op_sel_hi:[1,0,0]
	v_pk_fma_f32 v[160:161], v[64:65], s[74:75], v[160:161] op_sel_hi:[1,0,0]
	v_add_f32_e32 v64, v223, v224
	s_add_u32 s0, s0, 2
	v_fmac_f32_e32 v64, v201, v186
	v_add_f32_e32 v186, v226, v227
	s_addc_u32 s1, s1, 0
	s_add_i32 s8, s0, -1
	v_fmac_f32_e32 v186, v64, v225
	s_cmp_ge_i32 s8, s82
	v_lshl_add_u64 v[180:181], v[180:181], 0, s[78:79]
	s_waitcnt lgkmcnt(0)
	s_cbranch_scc1 .Lrot_exit_438
	v_mov_b32_e32 v201, v162
	s_barrier
	s_branch .LBB0_438
